# v28_nowait
# baseline (speedup 1.0000x reference)
; DI void dsa_item(const Params& p, int b, int blk) {
;     ...
;   for (int qq4x = 0; qq4x < 4 * REP_ATTN; ++qq4x) {
;     const int qq4 = qq4x & 3;
;     const int qq = w * 4 + qq4;
;     const int t = q0 + qq;
;     if (t >= LVALID) continue;
;     const size_t row = rowbase + t;
;     const int cnt = min((int)selcnt[qq], TOPK);
;     const u16* qptr = Aq + row * 512 + (lane & 3) * 64;
;     bf16x8 qa[8], qb[8];
;     #pragma unroll
;     for (int c = 0; c < 8; ++c) { qa[c] = ldg<bf16x8>(qptr + c * 8); qb[c] = ldg<bf16x8>(qptr + 256 + c * 8); }
;     float sc[4][8];
;     bf16x8 ka[2][8], kb[2][8];
;     bool valid[4];
;     {
;       const int ks = lane;
;       valid[0] = ks < cnt;
;       const int idx = valid[0] ? (int)sel[qq * 256 + ks] : 0;
;       const u16* kptr = Ak + (rowbase + idx) * 128;
;       #pragma unroll
;       for (int c = 0; c < 8; ++c) { ka[0][c] = ldg<bf16x8>(kptr + c * 8); kb[0][c] = ldg<bf16x8>(kptr + 64 + c * 8); }
;     }
;     #pragma unroll
;     for (int rd = 0; rd < 4; ++rd) {
;       if (rd < 3) {
;         const int ks = (rd + 1) * 64 + lane;
;         valid[rd + 1] = ks < cnt;
;         const int idx = valid[rd + 1] ? (int)sel[qq * 256 + ks] : 0;
;         const u16* kptr = Ak + (rowbase + idx) * 128;
;         #pragma unroll
;         for (int c = 0; c < 8; ++c) { ka[(rd + 1) & 1][c] = ldg<bf16x8>(kptr + c * 8); kb[(rd + 1) & 1][c] = ldg<bf16x8>(kptr + 64 + c * 8); }
;     ...
;     {
;       const u32x4 si = *(const u32x4*)(sel + qq * 256 + 8 * g16);
;       #pragma unroll
;       for (int j = 0; j < 8; ++j) {
;         const int ks = 8 * g16 + j;
;         const int idx = ks < cnt ? (int)((si[j >> 1] >> (16 * (j & 1))) & 0xffffu) : 0;
;         vr[j] = ldg<u32x4>(Av + (rowbase + idx) * 128 + n16 * 8);
;       }
;     }
.LBB0_1667:
	v_add_u32_e32 v66, s24, v158
	v_add_u32_e32 v2, s36, v66
	s_movk_i32 s4, 0x2010
	v_cmp_gt_i32_e32 vcc, s4, v2
	s_and_saveexec_b64 s[4:5], vcc
	s_cbranch_execz .LBB0_1666
	v_ashrrev_i32_e32 v3, 31, v2
	v_lshl_add_u32 v0, v66, 2, 0
	v_add_u32_e32 v0, 0x1ca80, v0
	ds_read_b32 v0, v0
	v_and_b32_e32 v130, 15, v187
	v_lshlrev_b32_e32 v133, 9, v66
	v_lshl_add_u32 v133, v130, 1, v133
	v_add_u32_e32 v133, 0x10000, v133
	ds_read_u16 v18, v133
	ds_read_u16 v22, v133 offset:32
	ds_read_u16 v26, v133 offset:64
	ds_read_u16 v30, v133 offset:96
	ds_read_u16 v34, v133 offset:128
	ds_read_u16 v38, v133 offset:160
	ds_read_u16 v42, v133 offset:192
	ds_read_u16 v46, v133 offset:224
	ds_read_u16 v50, v133 offset:256
	ds_read_u16 v54, v133 offset:288
	ds_read_u16 v58, v133 offset:320
	ds_read_u16 v62, v133 offset:352
	ds_read_u16 v66, v133 offset:384
	ds_read_u16 v70, v133 offset:416
	ds_read_u16 v74, v133 offset:448
	ds_read_u16 v78, v133 offset:480
	v_lshl_add_u64 v[152:153], s[16:17], 0, v[2:3]
	v_and_b32_e32 v142, 12, v187
	v_lshlrev_b32_e32 v142, 7, v142
	v_and_b32_e32 v144, 48, v187
	v_or_b32_e32 v142, v142, v144
	v_mov_b32_e32 v143, 0
	v_mov_b32_e32 v145, 0
	v_lshl_add_u64 v[134:135], s[0:1], 0, v[144:145]
	v_lshlrev_b64 v[4:5], 10, v[152:153]
	v_lshl_add_u64 v[4:5], v[146:147], 0, v[4:5]
	v_lshl_add_u64 v[142:143], v[4:5], 0, v[142:143]
	v_xor_b32_e32 v136, 16, v187
	v_lshlrev_b32_e32 v136, 2, v136
	v_xor_b32_e32 v137, 32, v187
	v_lshlrev_b32_e32 v137, 2, v137
	v_lshrrev_b32_e32 v138, 6, v178
	v_lshlrev_b32_e32 v138, 13, v138
	v_mul_u32_u24_e32 v252, 0x210, v130
	v_add3_u32 v138, v138, v252, v156
	v_mov_b32_e32 v139, 0xf149f2ca
	v_mov_b32_e32 v141, 0
	v_mov_b32_e32 v2, 0
	v_mov_b32_e32 v3, 0
	v_mov_b32_e32 v4, 0
	v_mov_b32_e32 v5, 0
	v_mov_b32_e32 v6, 0
	v_mov_b32_e32 v7, 0
	v_mov_b32_e32 v8, 0
	v_mov_b32_e32 v9, 0
	v_mov_b32_e32 v10, 0
	v_mov_b32_e32 v11, 0
	v_mov_b32_e32 v12, 0
	v_mov_b32_e32 v13, 0
	v_mov_b32_e32 v14, 0
	v_mov_b32_e32 v15, 0
	v_mov_b32_e32 v16, 0
	v_mov_b32_e32 v17, 0
	s_mov_b32 exec_lo, 0x000f000f
	s_mov_b32 exec_hi, 0x000f000f
	global_load_dwordx4 v[2:5], v[142:143], off
	global_load_dwordx4 v[6:9], v[142:143], off offset:64
	s_mov_b32 exec_lo, 0x00f000f0
	s_mov_b32 exec_hi, 0x00f000f0
	global_load_dwordx4 v[10:13], v[142:143], off
	global_load_dwordx4 v[14:17], v[142:143], off offset:64
	s_mov_b64 exec, -1
	s_waitcnt lgkmcnt(0)
	v_min_i32_e32 v206, 0x100, v0
	v_sub_u32_e32 v131, v206, v130
	v_lshrrev_b32_e32 v132, 1, v156
	v_sub_u32_e32 v132, v206, v132
	v_readfirstlane_b32 s100, v206
	v_add_u32_e32 v242, 0xffffffc0, v188
	v_mov_b32_e32 v241, 0
	ds_read_b128 v[248:251], v242
	s_waitcnt lgkmcnt(0)
	v_cmp_lt_i32_e32 vcc, v156, v206
	s_nop 1
	v_cndmask_b32_sdwa v240, v1, v248, vcc dst_sel:DWORD dst_unused:UNUSED_PAD src0_sel:DWORD src1_sel:WORD_0
	v_cmp_lt_i32_e32 vcc, v192, v206
	v_lshl_add_u64 v[244:245], s[16:17], 0, v[240:241]
	v_lshlrev_b64 v[244:245], 8, v[244:245]
	v_lshl_add_u64 v[244:245], v[148:149], 0, v[244:245]
	global_load_dwordx4 v[208:211], v[244:245], off
	v_cndmask_b32_sdwa v240, v1, v248, vcc dst_sel:DWORD dst_unused:UNUSED_PAD src0_sel:DWORD src1_sel:WORD_1
	v_cmp_lt_i32_e32 vcc, v193, v206
	v_lshl_add_u64 v[246:247], s[16:17], 0, v[240:241]
	v_lshlrev_b64 v[246:247], 8, v[246:247]
	v_lshl_add_u64 v[246:247], v[148:149], 0, v[246:247]
	global_load_dwordx4 v[212:215], v[246:247], off
	v_cndmask_b32_sdwa v240, v1, v249, vcc dst_sel:DWORD dst_unused:UNUSED_PAD src0_sel:DWORD src1_sel:WORD_0
	v_cmp_lt_i32_e32 vcc, v194, v206
	v_lshl_add_u64 v[244:245], s[16:17], 0, v[240:241]
	v_lshlrev_b64 v[244:245], 8, v[244:245]
	v_lshl_add_u64 v[244:245], v[148:149], 0, v[244:245]
	global_load_dwordx4 v[216:219], v[244:245], off
	v_cndmask_b32_sdwa v240, v1, v249, vcc dst_sel:DWORD dst_unused:UNUSED_PAD src0_sel:DWORD src1_sel:WORD_1
	v_cmp_lt_i32_e32 vcc, v157, v206
	v_lshl_add_u64 v[246:247], s[16:17], 0, v[240:241]
	v_lshlrev_b64 v[246:247], 8, v[246:247]
	v_lshl_add_u64 v[246:247], v[148:149], 0, v[246:247]
	global_load_dwordx4 v[220:223], v[246:247], off
	v_cndmask_b32_sdwa v240, v1, v250, vcc dst_sel:DWORD dst_unused:UNUSED_PAD src0_sel:DWORD src1_sel:WORD_0
	v_cmp_lt_i32_e32 vcc, v195, v206
	v_lshl_add_u64 v[244:245], s[16:17], 0, v[240:241]
	v_lshlrev_b64 v[244:245], 8, v[244:245]
	v_lshl_add_u64 v[244:245], v[148:149], 0, v[244:245]
	global_load_dwordx4 v[224:227], v[244:245], off
	v_cndmask_b32_sdwa v240, v1, v250, vcc dst_sel:DWORD dst_unused:UNUSED_PAD src0_sel:DWORD src1_sel:WORD_1
	v_cmp_lt_i32_e32 vcc, v196, v206
	v_lshl_add_u64 v[246:247], s[16:17], 0, v[240:241]
	v_lshlrev_b64 v[246:247], 8, v[246:247]
	v_lshl_add_u64 v[246:247], v[148:149], 0, v[246:247]
	global_load_dwordx4 v[228:231], v[246:247], off
	v_cndmask_b32_sdwa v240, v1, v251, vcc dst_sel:DWORD dst_unused:UNUSED_PAD src0_sel:DWORD src1_sel:WORD_0
	v_cmp_lt_i32_e32 vcc, v197, v206
	v_lshl_add_u64 v[244:245], s[16:17], 0, v[240:241]
	v_lshlrev_b64 v[244:245], 8, v[244:245]
	v_lshl_add_u64 v[244:245], v[148:149], 0, v[244:245]
	global_load_dwordx4 v[232:235], v[244:245], off
	v_cndmask_b32_sdwa v240, v1, v251, vcc dst_sel:DWORD dst_unused:UNUSED_PAD src0_sel:DWORD src1_sel:WORD_1
	v_lshl_add_u64 v[246:247], s[16:17], 0, v[240:241]
	v_lshlrev_b64 v[246:247], 8, v[246:247]
	v_lshl_add_u64 v[246:247], v[148:149], 0, v[246:247]
	global_load_dwordx4 v[236:239], v[246:247], off
	v_cmp_lt_i32_e32 vcc, 0, v131
	s_nop 1
	v_cndmask_b32_e32 v140, v1, v18, vcc
	v_lshl_add_u64 v[142:143], s[16:17], 0, v[140:141]
	v_lshlrev_b64 v[142:143], 8, v[142:143]
	v_lshl_add_u64 v[142:143], v[134:135], 0, v[142:143]
	global_load_dwordx4 v[82:85], v[142:143], off
	global_load_dwordx4 v[86:89], v[142:143], off offset:64
	global_load_dwordx4 v[90:93], v[142:143], off offset:128
	global_load_dwordx4 v[94:97], v[142:143], off offset:192
	v_cmp_lt_i32_e32 vcc, 16, v131
	s_nop 1
	v_cndmask_b32_e32 v140, v1, v22, vcc
	v_lshl_add_u64 v[144:145], s[16:17], 0, v[140:141]
	v_lshlrev_b64 v[144:145], 8, v[144:145]
	v_lshl_add_u64 v[144:145], v[134:135], 0, v[144:145]
	global_load_dwordx4 v[98:101], v[144:145], off
	global_load_dwordx4 v[102:105], v[144:145], off offset:64
	global_load_dwordx4 v[106:109], v[144:145], off offset:128
	global_load_dwordx4 v[110:113], v[144:145], off offset:192
	v_cmp_lt_i32_e32 vcc, 32, v131
	s_nop 1
	v_cndmask_b32_e32 v140, v1, v26, vcc
	v_lshl_add_u64 v[142:143], s[16:17], 0, v[140:141]
	v_lshlrev_b64 v[142:143], 8, v[142:143]
	v_lshl_add_u64 v[142:143], v[134:135], 0, v[142:143]
	global_load_dwordx4 v[114:117], v[142:143], off
	global_load_dwordx4 v[118:121], v[142:143], off offset:64
	global_load_dwordx4 v[122:125], v[142:143], off offset:128
	global_load_dwordx4 v[126:129], v[142:143], off offset:192
	s_waitcnt vmcnt(8)
; #define MFMA4(a, b, c)  __builtin_amdgcn_mfma_f32_4x4x4bf16_1k((a), (b), (c), 0, 0, 0)
; DI void dsa_item(const Params& p, int b, int blk) {
;     ...
;     #pragma unroll
;     for (int rd = 0; rd < 4; ++rd) {
;       if (rd < 3) {
;         const int ks = (rd + 1) * 64 + lane;
;         valid[rd + 1] = ks < cnt;
;         const int idx = valid[rd + 1] ? (int)sel[qq * 256 + ks] : 0;
;         const u16* kptr = Ak + (rowbase + idx) * 128;
;         #pragma unroll
;         for (int c = 0; c < 8; ++c) { ka[(rd + 1) & 1][c] = ldg<bf16x8>(kptr + c * 8); kb[(rd + 1) & 1][c] = ldg<bf16x8>(kptr + 64 + c * 8); }
;       }
;       f32x4 c0 = {0.f, 0.f, 0.f, 0.f}, c1 = {0.f, 0.f, 0.f, 0.f};
;       #pragma unroll
;       for (int c = 0; c < 8; ++c) {
;         const bf16x8 kav = ka[rd & 1][c], kbv = kb[rd & 1][c];
;         s16x4 qlo = {qa[c][0], qa[c][1], qa[c][2], qa[c][3]}, qhi = {qa[c][4], qa[c][5], qa[c][6], qa[c][7]};
;         s16x4 klo = {kav[0], kav[1], kav[2], kav[3]}, khi = {kav[4], kav[5], kav[6], kav[7]};
;         c0 = MFMA4(qlo, klo, c0); c0 = MFMA4(qhi, khi, c0);
;         s16x4 rlo = {qb[c][0], qb[c][1], qb[c][2], qb[c][3]}, rhi = {qb[c][4], qb[c][5], qb[c][6], qb[c][7]};
;         s16x4 llo = {kbv[0], kbv[1], kbv[2], kbv[3]}, lhi = {kbv[4], kbv[5], kbv[6], kbv[7]};
;         c1 = MFMA4(rlo, llo, c1); c1 = MFMA4(rhi, lhi, c1);
;       }
;       #pragma unroll
;       for (int m = 0; m < 4; ++m) { sc[rd][m] = valid[rd] ? c0[m] * SSC : -1e30f; sc[rd][4 + m] = valid[rd] ? c1[m] * SSC : -1e30f; }
;     }
	v_mfma_f32_16x16x32_bf16 v[18:21], v[82:85], v[2:5], 0
	v_mfma_f32_16x16x32_bf16 v[18:21], v[86:89], v[6:9], v[18:21]
	v_mfma_f32_16x16x32_bf16 v[18:21], v[90:93], v[10:13], v[18:21]
	v_mfma_f32_16x16x32_bf16 v[18:21], v[94:97], v[14:17], v[18:21]
	v_cmp_lt_i32_e32 vcc, 48, v131
	s_nop 1
	v_cndmask_b32_e32 v140, v1, v30, vcc
	v_lshl_add_u64 v[144:145], s[16:17], 0, v[140:141]
	v_lshlrev_b64 v[144:145], 8, v[144:145]
	v_lshl_add_u64 v[144:145], v[134:135], 0, v[144:145]
	global_load_dwordx4 v[82:85], v[144:145], off
	global_load_dwordx4 v[86:89], v[144:145], off offset:64
	global_load_dwordx4 v[90:93], v[144:145], off offset:128
	global_load_dwordx4 v[94:97], v[144:145], off offset:192
	s_waitcnt vmcnt(8)
	v_mfma_f32_16x16x32_bf16 v[22:25], v[98:101], v[2:5], 0
	v_mfma_f32_16x16x32_bf16 v[22:25], v[102:105], v[6:9], v[22:25]
	v_mfma_f32_16x16x32_bf16 v[22:25], v[106:109], v[10:13], v[22:25]
	v_mfma_f32_16x16x32_bf16 v[22:25], v[110:113], v[14:17], v[22:25]
	v_cmp_lt_i32_e32 vcc, 64, v131
	s_nop 1
	v_cndmask_b32_e32 v140, v1, v34, vcc
	v_lshl_add_u64 v[142:143], s[16:17], 0, v[140:141]
	v_lshlrev_b64 v[142:143], 8, v[142:143]
	v_lshl_add_u64 v[142:143], v[134:135], 0, v[142:143]
	global_load_dwordx4 v[98:101], v[142:143], off
	global_load_dwordx4 v[102:105], v[142:143], off offset:64
	global_load_dwordx4 v[106:109], v[142:143], off offset:128
	global_load_dwordx4 v[110:113], v[142:143], off offset:192
	s_waitcnt vmcnt(8)
	v_mfma_f32_16x16x32_bf16 v[26:29], v[114:117], v[2:5], 0
	v_mfma_f32_16x16x32_bf16 v[26:29], v[118:121], v[6:9], v[26:29]
	v_mfma_f32_16x16x32_bf16 v[26:29], v[122:125], v[10:13], v[26:29]
	v_mfma_f32_16x16x32_bf16 v[26:29], v[126:129], v[14:17], v[26:29]
	v_cmp_lt_i32_e32 vcc, 0x50, v131
	s_nop 1
	v_cndmask_b32_e32 v140, v1, v38, vcc
	v_lshl_add_u64 v[144:145], s[16:17], 0, v[140:141]
	v_lshlrev_b64 v[144:145], 8, v[144:145]
	v_lshl_add_u64 v[144:145], v[134:135], 0, v[144:145]
	global_load_dwordx4 v[114:117], v[144:145], off
	global_load_dwordx4 v[118:121], v[144:145], off offset:64
	global_load_dwordx4 v[122:125], v[144:145], off offset:128
	global_load_dwordx4 v[126:129], v[144:145], off offset:192
	s_waitcnt vmcnt(8)
	v_mfma_f32_16x16x32_bf16 v[30:33], v[82:85], v[2:5], 0
	v_mfma_f32_16x16x32_bf16 v[30:33], v[86:89], v[6:9], v[30:33]
	v_mfma_f32_16x16x32_bf16 v[30:33], v[90:93], v[10:13], v[30:33]
	v_mfma_f32_16x16x32_bf16 v[30:33], v[94:97], v[14:17], v[30:33]
	v_cmp_lt_i32_e32 vcc, 0x60, v131
	s_nop 1
	v_cndmask_b32_e32 v140, v1, v42, vcc
	v_lshl_add_u64 v[142:143], s[16:17], 0, v[140:141]
	v_lshlrev_b64 v[142:143], 8, v[142:143]
	v_lshl_add_u64 v[142:143], v[134:135], 0, v[142:143]
	global_load_dwordx4 v[82:85], v[142:143], off
	global_load_dwordx4 v[86:89], v[142:143], off offset:64
	global_load_dwordx4 v[90:93], v[142:143], off offset:128
	global_load_dwordx4 v[94:97], v[142:143], off offset:192
	s_waitcnt vmcnt(8)
	v_mfma_f32_16x16x32_bf16 v[34:37], v[98:101], v[2:5], 0
	v_mfma_f32_16x16x32_bf16 v[34:37], v[102:105], v[6:9], v[34:37]
	v_mfma_f32_16x16x32_bf16 v[34:37], v[106:109], v[10:13], v[34:37]
	v_mfma_f32_16x16x32_bf16 v[34:37], v[110:113], v[14:17], v[34:37]
	v_cmp_lt_i32_e32 vcc, 0x70, v131
	s_nop 1
	v_cndmask_b32_e32 v140, v1, v46, vcc
	v_lshl_add_u64 v[144:145], s[16:17], 0, v[140:141]
	v_lshlrev_b64 v[144:145], 8, v[144:145]
	v_lshl_add_u64 v[144:145], v[134:135], 0, v[144:145]
	global_load_dwordx4 v[98:101], v[144:145], off
	global_load_dwordx4 v[102:105], v[144:145], off offset:64
	global_load_dwordx4 v[106:109], v[144:145], off offset:128
	global_load_dwordx4 v[110:113], v[144:145], off offset:192
	s_waitcnt vmcnt(8)
	v_mfma_f32_16x16x32_bf16 v[38:41], v[114:117], v[2:5], 0
	v_mfma_f32_16x16x32_bf16 v[38:41], v[118:121], v[6:9], v[38:41]
	v_mfma_f32_16x16x32_bf16 v[38:41], v[122:125], v[10:13], v[38:41]
	v_mfma_f32_16x16x32_bf16 v[38:41], v[126:129], v[14:17], v[38:41]
	v_cmp_lt_i32_e32 vcc, 0x80, v131
	s_nop 1
	v_cndmask_b32_e32 v140, v1, v50, vcc
	v_lshl_add_u64 v[142:143], s[16:17], 0, v[140:141]
	v_lshlrev_b64 v[142:143], 8, v[142:143]
	v_lshl_add_u64 v[142:143], v[134:135], 0, v[142:143]
	global_load_dwordx4 v[114:117], v[142:143], off
	global_load_dwordx4 v[118:121], v[142:143], off offset:64
	global_load_dwordx4 v[122:125], v[142:143], off offset:128
	global_load_dwordx4 v[126:129], v[142:143], off offset:192
	s_waitcnt vmcnt(8)
	v_mfma_f32_16x16x32_bf16 v[42:45], v[82:85], v[2:5], 0
	v_mfma_f32_16x16x32_bf16 v[42:45], v[86:89], v[6:9], v[42:45]
	v_mfma_f32_16x16x32_bf16 v[42:45], v[90:93], v[10:13], v[42:45]
	v_mfma_f32_16x16x32_bf16 v[42:45], v[94:97], v[14:17], v[42:45]
	v_cmp_lt_i32_e32 vcc, 0x90, v131
	s_nop 1
	v_cndmask_b32_e32 v140, v1, v54, vcc
	v_lshl_add_u64 v[144:145], s[16:17], 0, v[140:141]
	v_lshlrev_b64 v[144:145], 8, v[144:145]
	v_lshl_add_u64 v[144:145], v[134:135], 0, v[144:145]
	global_load_dwordx4 v[82:85], v[144:145], off
	global_load_dwordx4 v[86:89], v[144:145], off offset:64
	global_load_dwordx4 v[90:93], v[144:145], off offset:128
	global_load_dwordx4 v[94:97], v[144:145], off offset:192
	s_waitcnt vmcnt(8)
	v_mfma_f32_16x16x32_bf16 v[46:49], v[98:101], v[2:5], 0
	v_mfma_f32_16x16x32_bf16 v[46:49], v[102:105], v[6:9], v[46:49]
	v_mfma_f32_16x16x32_bf16 v[46:49], v[106:109], v[10:13], v[46:49]
	v_mfma_f32_16x16x32_bf16 v[46:49], v[110:113], v[14:17], v[46:49]
	v_cmp_lt_i32_e32 vcc, 0xa0, v131
	s_nop 1
	v_cndmask_b32_e32 v140, v1, v58, vcc
	v_lshl_add_u64 v[142:143], s[16:17], 0, v[140:141]
	v_lshlrev_b64 v[142:143], 8, v[142:143]
	v_lshl_add_u64 v[142:143], v[134:135], 0, v[142:143]
	global_load_dwordx4 v[98:101], v[142:143], off
	global_load_dwordx4 v[102:105], v[142:143], off offset:64
	global_load_dwordx4 v[106:109], v[142:143], off offset:128
	global_load_dwordx4 v[110:113], v[142:143], off offset:192
	s_waitcnt vmcnt(8)
; #define MFMA4(a, b, c)  __builtin_amdgcn_mfma_f32_4x4x4bf16_1k((a), (b), (c), 0, 0, 0)
; DI void dsa_item(const Params& p, int b, int blk) {
;     ...
;     #pragma unroll
;     for (int rd = 0; rd < 4; ++rd) {
;       if (rd < 3) {
;         const int ks = (rd + 1) * 64 + lane;
;         valid[rd + 1] = ks < cnt;
;         const int idx = valid[rd + 1] ? (int)sel[qq * 256 + ks] : 0;
;         const u16* kptr = Ak + (rowbase + idx) * 128;
;         #pragma unroll
;         for (int c = 0; c < 8; ++c) { ka[(rd + 1) & 1][c] = ldg<bf16x8>(kptr + c * 8); kb[(rd + 1) & 1][c] = ldg<bf16x8>(kptr + 64 + c * 8); }
;       }
;       f32x4 c0 = {0.f, 0.f, 0.f, 0.f}, c1 = {0.f, 0.f, 0.f, 0.f};
;       #pragma unroll
;       for (int c = 0; c < 8; ++c) {
;         const bf16x8 kav = ka[rd & 1][c], kbv = kb[rd & 1][c];
;         s16x4 qlo = {qa[c][0], qa[c][1], qa[c][2], qa[c][3]}, qhi = {qa[c][4], qa[c][5], qa[c][6], qa[c][7]};
;         s16x4 klo = {kav[0], kav[1], kav[2], kav[3]}, khi = {kav[4], kav[5], kav[6], kav[7]};
;         c0 = MFMA4(qlo, klo, c0); c0 = MFMA4(qhi, khi, c0);
;         s16x4 rlo = {qb[c][0], qb[c][1], qb[c][2], qb[c][3]}, rhi = {qb[c][4], qb[c][5], qb[c][6], qb[c][7]};
;         s16x4 llo = {kbv[0], kbv[1], kbv[2], kbv[3]}, lhi = {kbv[4], kbv[5], kbv[6], kbv[7]};
;         c1 = MFMA4(rlo, llo, c1); c1 = MFMA4(rhi, lhi, c1);
;       }
	v_mfma_f32_16x16x32_bf16 v[50:53], v[114:117], v[2:5], 0
	v_mfma_f32_16x16x32_bf16 v[50:53], v[118:121], v[6:9], v[50:53]
	v_mfma_f32_16x16x32_bf16 v[50:53], v[122:125], v[10:13], v[50:53]
	v_mfma_f32_16x16x32_bf16 v[50:53], v[126:129], v[14:17], v[50:53]
	v_cmp_lt_i32_e32 vcc, 0xb0, v131
	s_nop 1
	v_cndmask_b32_e32 v140, v1, v62, vcc
	v_lshl_add_u64 v[144:145], s[16:17], 0, v[140:141]
	v_lshlrev_b64 v[144:145], 8, v[144:145]
	v_lshl_add_u64 v[144:145], v[134:135], 0, v[144:145]
	global_load_dwordx4 v[114:117], v[144:145], off
	global_load_dwordx4 v[118:121], v[144:145], off offset:64
	global_load_dwordx4 v[122:125], v[144:145], off offset:128
	global_load_dwordx4 v[126:129], v[144:145], off offset:192
	s_waitcnt vmcnt(8)
	v_mfma_f32_16x16x32_bf16 v[54:57], v[82:85], v[2:5], 0
	v_mfma_f32_16x16x32_bf16 v[54:57], v[86:89], v[6:9], v[54:57]
	v_mfma_f32_16x16x32_bf16 v[54:57], v[90:93], v[10:13], v[54:57]
	v_mfma_f32_16x16x32_bf16 v[54:57], v[94:97], v[14:17], v[54:57]
	v_cmp_lt_i32_e32 vcc, 0xc0, v131
	s_nop 1
	v_cndmask_b32_e32 v140, v1, v66, vcc
	v_lshl_add_u64 v[142:143], s[16:17], 0, v[140:141]
	v_lshlrev_b64 v[142:143], 8, v[142:143]
	v_lshl_add_u64 v[142:143], v[134:135], 0, v[142:143]
	global_load_dwordx4 v[82:85], v[142:143], off
	global_load_dwordx4 v[86:89], v[142:143], off offset:64
	global_load_dwordx4 v[90:93], v[142:143], off offset:128
	global_load_dwordx4 v[94:97], v[142:143], off offset:192
	s_waitcnt vmcnt(8)
	v_mfma_f32_16x16x32_bf16 v[58:61], v[98:101], v[2:5], 0
	v_mfma_f32_16x16x32_bf16 v[58:61], v[102:105], v[6:9], v[58:61]
	v_mfma_f32_16x16x32_bf16 v[58:61], v[106:109], v[10:13], v[58:61]
	v_mfma_f32_16x16x32_bf16 v[58:61], v[110:113], v[14:17], v[58:61]
	v_cmp_lt_i32_e32 vcc, 0xd0, v131
	s_nop 1
	v_cndmask_b32_e32 v140, v1, v70, vcc
	v_lshl_add_u64 v[144:145], s[16:17], 0, v[140:141]
	v_lshlrev_b64 v[144:145], 8, v[144:145]
	v_lshl_add_u64 v[144:145], v[134:135], 0, v[144:145]
	global_load_dwordx4 v[98:101], v[144:145], off
	global_load_dwordx4 v[102:105], v[144:145], off offset:64
	global_load_dwordx4 v[106:109], v[144:145], off offset:128
	global_load_dwordx4 v[110:113], v[144:145], off offset:192
	s_waitcnt vmcnt(8)
	v_mfma_f32_16x16x32_bf16 v[62:65], v[114:117], v[2:5], 0
	v_mfma_f32_16x16x32_bf16 v[62:65], v[118:121], v[6:9], v[62:65]
	v_mfma_f32_16x16x32_bf16 v[62:65], v[122:125], v[10:13], v[62:65]
	v_mfma_f32_16x16x32_bf16 v[62:65], v[126:129], v[14:17], v[62:65]
	v_cmp_lt_i32_e32 vcc, 0xe0, v131
	s_nop 1
	v_cndmask_b32_e32 v140, v1, v74, vcc
	v_lshl_add_u64 v[142:143], s[16:17], 0, v[140:141]
	v_lshlrev_b64 v[142:143], 8, v[142:143]
	v_lshl_add_u64 v[142:143], v[134:135], 0, v[142:143]
	global_load_dwordx4 v[114:117], v[142:143], off
	global_load_dwordx4 v[118:121], v[142:143], off offset:64
	global_load_dwordx4 v[122:125], v[142:143], off offset:128
	global_load_dwordx4 v[126:129], v[142:143], off offset:192
	s_waitcnt vmcnt(8)
	v_mfma_f32_16x16x32_bf16 v[66:69], v[82:85], v[2:5], 0
	v_mfma_f32_16x16x32_bf16 v[66:69], v[86:89], v[6:9], v[66:69]
	v_mfma_f32_16x16x32_bf16 v[66:69], v[90:93], v[10:13], v[66:69]
	v_mfma_f32_16x16x32_bf16 v[66:69], v[94:97], v[14:17], v[66:69]
	v_cmp_lt_i32_e32 vcc, 0xf0, v131
	s_nop 1
	v_cndmask_b32_e32 v140, v1, v78, vcc
	v_lshl_add_u64 v[144:145], s[16:17], 0, v[140:141]
	v_lshlrev_b64 v[144:145], 8, v[144:145]
	v_lshl_add_u64 v[144:145], v[134:135], 0, v[144:145]
	global_load_dwordx4 v[82:85], v[144:145], off
	global_load_dwordx4 v[86:89], v[144:145], off offset:64
	global_load_dwordx4 v[90:93], v[144:145], off offset:128
	global_load_dwordx4 v[94:97], v[144:145], off offset:192
	s_waitcnt vmcnt(8)
	v_mfma_f32_16x16x32_bf16 v[70:73], v[98:101], v[2:5], 0
	v_mfma_f32_16x16x32_bf16 v[70:73], v[102:105], v[6:9], v[70:73]
	v_mfma_f32_16x16x32_bf16 v[70:73], v[106:109], v[10:13], v[70:73]
	v_mfma_f32_16x16x32_bf16 v[70:73], v[110:113], v[14:17], v[70:73]
	s_waitcnt vmcnt(4)
	v_mfma_f32_16x16x32_bf16 v[74:77], v[114:117], v[2:5], 0
	v_mfma_f32_16x16x32_bf16 v[74:77], v[118:121], v[6:9], v[74:77]
	v_mfma_f32_16x16x32_bf16 v[74:77], v[122:125], v[10:13], v[74:77]
	v_mfma_f32_16x16x32_bf16 v[74:77], v[126:129], v[14:17], v[74:77]
	s_waitcnt vmcnt(0)
	v_mfma_f32_16x16x32_bf16 v[78:81], v[82:85], v[2:5], 0
	v_mfma_f32_16x16x32_bf16 v[78:81], v[86:89], v[6:9], v[78:81]
	v_mfma_f32_16x16x32_bf16 v[78:81], v[90:93], v[10:13], v[78:81]
	v_mfma_f32_16x16x32_bf16 v[78:81], v[94:97], v[14:17], v[78:81]
	v_mov_b32_e32 v8, v132
	v_mov_b32_e32 v9, v136
	v_mov_b32_e32 v10, v137
	ds_read_b128 v[12:15], v242 offset:64
	s_waitcnt lgkmcnt(0)
; DI void dsa_item(const Params& p, int b, int blk) {
;     ...
;       for (int m = 0; m < 4; ++m) { sc[rd][m] = valid[rd] ? c0[m] * SSC : -1e30f; sc[rd][4 + m] = valid[rd] ? c1[m] * SSC : -1e30f; }
;     ...
;       if (kc < 7) {
;         const u32x4 si = *(const u32x4*)(sel + qq * 256 + (kc + 1) * 32 + 8 * g16);
;         #pragma unroll
;         for (int j = 0; j < 8; ++j) {
;           const int ks = (kc + 1) * 32 + 8 * g16 + j;
;           const int idx = ks < cnt ? (int)((si[j >> 1] >> (16 * (j & 1))) & 0xffffu) : 0;
;           vr[j] = ldg<u32x4>(Av + (rowbase + idx) * 128 + n16 * 8);
;         }
;       }
	v_add_u32_e32 v243, 0xffffffe0, v206
	v_cmp_lt_i32_e32 vcc, v156, v243
	s_nop 1
	v_cndmask_b32_sdwa v240, v1, v12, vcc dst_sel:DWORD dst_unused:UNUSED_PAD src0_sel:DWORD src1_sel:WORD_0
	v_cmp_lt_i32_e32 vcc, v192, v243
	v_lshl_add_u64 v[244:245], s[16:17], 0, v[240:241]
	v_lshlrev_b64 v[244:245], 8, v[244:245]
	v_lshl_add_u64 v[244:245], v[148:149], 0, v[244:245]
	global_load_dwordx4 v[106:109], v[244:245], off
	v_cndmask_b32_sdwa v240, v1, v12, vcc dst_sel:DWORD dst_unused:UNUSED_PAD src0_sel:DWORD src1_sel:WORD_1
	v_cmp_lt_i32_e32 vcc, v193, v243
	v_lshl_add_u64 v[246:247], s[16:17], 0, v[240:241]
	v_lshlrev_b64 v[246:247], 8, v[246:247]
	v_lshl_add_u64 v[246:247], v[148:149], 0, v[246:247]
	global_load_dwordx4 v[110:113], v[246:247], off
	v_cndmask_b32_sdwa v240, v1, v13, vcc dst_sel:DWORD dst_unused:UNUSED_PAD src0_sel:DWORD src1_sel:WORD_0
	v_cmp_lt_i32_e32 vcc, v194, v243
	v_lshl_add_u64 v[244:245], s[16:17], 0, v[240:241]
	v_lshlrev_b64 v[244:245], 8, v[244:245]
	v_lshl_add_u64 v[244:245], v[148:149], 0, v[244:245]
	global_load_dwordx4 v[114:117], v[244:245], off
	v_cndmask_b32_sdwa v240, v1, v13, vcc dst_sel:DWORD dst_unused:UNUSED_PAD src0_sel:DWORD src1_sel:WORD_1
	v_cmp_lt_i32_e32 vcc, v157, v243
	v_lshl_add_u64 v[246:247], s[16:17], 0, v[240:241]
	v_lshlrev_b64 v[246:247], 8, v[246:247]
	v_lshl_add_u64 v[246:247], v[148:149], 0, v[246:247]
	global_load_dwordx4 v[118:121], v[246:247], off
	v_cndmask_b32_sdwa v240, v1, v14, vcc dst_sel:DWORD dst_unused:UNUSED_PAD src0_sel:DWORD src1_sel:WORD_0
	v_cmp_lt_i32_e32 vcc, v195, v243
	v_lshl_add_u64 v[244:245], s[16:17], 0, v[240:241]
	v_lshlrev_b64 v[244:245], 8, v[244:245]
	v_lshl_add_u64 v[244:245], v[148:149], 0, v[244:245]
	global_load_dwordx4 v[122:125], v[244:245], off
	v_cndmask_b32_sdwa v240, v1, v14, vcc dst_sel:DWORD dst_unused:UNUSED_PAD src0_sel:DWORD src1_sel:WORD_1
	v_cmp_lt_i32_e32 vcc, v196, v243
	v_lshl_add_u64 v[246:247], s[16:17], 0, v[240:241]
	v_lshlrev_b64 v[246:247], 8, v[246:247]
	v_lshl_add_u64 v[246:247], v[148:149], 0, v[246:247]
	global_load_dwordx4 v[126:129], v[246:247], off
	v_cndmask_b32_sdwa v240, v1, v15, vcc dst_sel:DWORD dst_unused:UNUSED_PAD src0_sel:DWORD src1_sel:WORD_0
	v_cmp_lt_i32_e32 vcc, v197, v243
	v_lshl_add_u64 v[244:245], s[16:17], 0, v[240:241]
	v_lshlrev_b64 v[244:245], 8, v[244:245]
	v_lshl_add_u64 v[244:245], v[148:149], 0, v[244:245]
	global_load_dwordx4 v[130:133], v[244:245], off
	v_cndmask_b32_sdwa v240, v1, v15, vcc dst_sel:DWORD dst_unused:UNUSED_PAD src0_sel:DWORD src1_sel:WORD_1
	v_lshl_add_u64 v[246:247], s[16:17], 0, v[240:241]
	v_lshlrev_b64 v[246:247], 8, v[246:247]
	v_lshl_add_u64 v[246:247], v[148:149], 0, v[246:247]
	global_load_dwordx4 v[134:137], v[246:247], off
	v_mul_f32_e32 v18, 0x3e38aa3b, v18
	v_mul_f32_e32 v19, 0x3e38aa3b, v19
	v_mul_f32_e32 v20, 0x3e38aa3b, v20
	v_mul_f32_e32 v21, 0x3e38aa3b, v21
	v_mul_f32_e32 v22, 0x3e38aa3b, v22
	v_mul_f32_e32 v23, 0x3e38aa3b, v23
	v_mul_f32_e32 v24, 0x3e38aa3b, v24
	v_mul_f32_e32 v25, 0x3e38aa3b, v25
	v_mul_f32_e32 v26, 0x3e38aa3b, v26
	v_mul_f32_e32 v27, 0x3e38aa3b, v27
	v_mul_f32_e32 v28, 0x3e38aa3b, v28
	v_mul_f32_e32 v29, 0x3e38aa3b, v29
	v_mul_f32_e32 v30, 0x3e38aa3b, v30
	v_mul_f32_e32 v31, 0x3e38aa3b, v31
	v_mul_f32_e32 v32, 0x3e38aa3b, v32
	v_mul_f32_e32 v33, 0x3e38aa3b, v33
	v_mul_f32_e32 v34, 0x3e38aa3b, v34
	v_mul_f32_e32 v35, 0x3e38aa3b, v35
	v_mul_f32_e32 v36, 0x3e38aa3b, v36
	v_mul_f32_e32 v37, 0x3e38aa3b, v37
	v_mul_f32_e32 v38, 0x3e38aa3b, v38
	v_mul_f32_e32 v39, 0x3e38aa3b, v39
	v_mul_f32_e32 v40, 0x3e38aa3b, v40
	v_mul_f32_e32 v41, 0x3e38aa3b, v41
	v_mul_f32_e32 v42, 0x3e38aa3b, v42
	v_mul_f32_e32 v43, 0x3e38aa3b, v43
	v_mul_f32_e32 v44, 0x3e38aa3b, v44
	v_mul_f32_e32 v45, 0x3e38aa3b, v45
	v_mul_f32_e32 v46, 0x3e38aa3b, v46
	v_mul_f32_e32 v47, 0x3e38aa3b, v47
	v_mul_f32_e32 v48, 0x3e38aa3b, v48
	v_mul_f32_e32 v49, 0x3e38aa3b, v49
	v_mul_f32_e32 v50, 0x3e38aa3b, v50
	v_mul_f32_e32 v51, 0x3e38aa3b, v51
	v_mul_f32_e32 v52, 0x3e38aa3b, v52
	v_mul_f32_e32 v53, 0x3e38aa3b, v53
	v_mul_f32_e32 v54, 0x3e38aa3b, v54
	v_mul_f32_e32 v55, 0x3e38aa3b, v55
	v_mul_f32_e32 v56, 0x3e38aa3b, v56
	v_mul_f32_e32 v57, 0x3e38aa3b, v57
	v_mul_f32_e32 v58, 0x3e38aa3b, v58
	v_mul_f32_e32 v59, 0x3e38aa3b, v59
	v_mul_f32_e32 v60, 0x3e38aa3b, v60
	v_mul_f32_e32 v61, 0x3e38aa3b, v61
	v_mul_f32_e32 v62, 0x3e38aa3b, v62
	v_mul_f32_e32 v63, 0x3e38aa3b, v63
	v_mul_f32_e32 v64, 0x3e38aa3b, v64
	v_mul_f32_e32 v65, 0x3e38aa3b, v65
	v_mul_f32_e32 v66, 0x3e38aa3b, v66
	v_mul_f32_e32 v67, 0x3e38aa3b, v67
	v_mul_f32_e32 v68, 0x3e38aa3b, v68
	v_mul_f32_e32 v69, 0x3e38aa3b, v69
	v_mul_f32_e32 v70, 0x3e38aa3b, v70
	v_mul_f32_e32 v71, 0x3e38aa3b, v71
	v_mul_f32_e32 v72, 0x3e38aa3b, v72
	v_mul_f32_e32 v73, 0x3e38aa3b, v73
	v_mul_f32_e32 v74, 0x3e38aa3b, v74
	v_mul_f32_e32 v75, 0x3e38aa3b, v75
	v_mul_f32_e32 v76, 0x3e38aa3b, v76
	v_mul_f32_e32 v77, 0x3e38aa3b, v77
	v_mul_f32_e32 v78, 0x3e38aa3b, v78
	v_mul_f32_e32 v79, 0x3e38aa3b, v79
	v_mul_f32_e32 v80, 0x3e38aa3b, v80
	v_mul_f32_e32 v81, 0x3e38aa3b, v81
	s_cmpk_ge_i32 s100, 0x100
	s_cbranch_scc1 .Lqk_nomask
; DI void dsa_item(const Params& p, int b, int blk) {
;     ...
;       for (int m = 0; m < 4; ++m) { sc[rd][m] = valid[rd] ? c0[m] * SSC : -1e30f; sc[rd][4 + m] = valid[rd] ? c1[m] * SSC : -1e30f; }
	v_cmp_lt_i32_e32 vcc, 0, v8
	s_nop 1
	v_cndmask_b32_e32 v18, v139, v18, vcc
	v_cmp_lt_i32_e32 vcc, 1, v8
	s_nop 1
	v_cndmask_b32_e32 v19, v139, v19, vcc
	v_cmp_lt_i32_e32 vcc, 2, v8
	s_nop 1
	v_cndmask_b32_e32 v20, v139, v20, vcc
	v_cmp_lt_i32_e32 vcc, 3, v8
	s_nop 1
	v_cndmask_b32_e32 v21, v139, v21, vcc
	v_cmp_lt_i32_e32 vcc, 16, v8
	s_nop 1
	v_cndmask_b32_e32 v22, v139, v22, vcc
	v_cmp_lt_i32_e32 vcc, 17, v8
	s_nop 1
	v_cndmask_b32_e32 v23, v139, v23, vcc
	v_cmp_lt_i32_e32 vcc, 18, v8
	s_nop 1
	v_cndmask_b32_e32 v24, v139, v24, vcc
	v_cmp_lt_i32_e32 vcc, 19, v8
	s_nop 1
	v_cndmask_b32_e32 v25, v139, v25, vcc
	v_cmp_lt_i32_e32 vcc, 32, v8
	s_nop 1
	v_cndmask_b32_e32 v26, v139, v26, vcc
	v_cmp_lt_i32_e32 vcc, 33, v8
	s_nop 1
	v_cndmask_b32_e32 v27, v139, v27, vcc
	v_cmp_lt_i32_e32 vcc, 34, v8
	s_nop 1
	v_cndmask_b32_e32 v28, v139, v28, vcc
	v_cmp_lt_i32_e32 vcc, 35, v8
	s_nop 1
	v_cndmask_b32_e32 v29, v139, v29, vcc
	v_cmp_lt_i32_e32 vcc, 48, v8
	s_nop 1
	v_cndmask_b32_e32 v30, v139, v30, vcc
	v_cmp_lt_i32_e32 vcc, 49, v8
	s_nop 1
	v_cndmask_b32_e32 v31, v139, v31, vcc
	v_cmp_lt_i32_e32 vcc, 50, v8
	s_nop 1
	v_cndmask_b32_e32 v32, v139, v32, vcc
	v_cmp_lt_i32_e32 vcc, 51, v8
	s_nop 1
	v_cndmask_b32_e32 v33, v139, v33, vcc
	v_cmp_lt_i32_e32 vcc, 64, v8
	s_nop 1
	v_cndmask_b32_e32 v34, v139, v34, vcc
	v_cmp_lt_i32_e32 vcc, 0x41, v8
	s_nop 1
	v_cndmask_b32_e32 v35, v139, v35, vcc
	v_cmp_lt_i32_e32 vcc, 0x42, v8
	s_nop 1
	v_cndmask_b32_e32 v36, v139, v36, vcc
	v_cmp_lt_i32_e32 vcc, 0x43, v8
	s_nop 1
	v_cndmask_b32_e32 v37, v139, v37, vcc
	v_cmp_lt_i32_e32 vcc, 0x50, v8
	s_nop 1
	v_cndmask_b32_e32 v38, v139, v38, vcc
	v_cmp_lt_i32_e32 vcc, 0x51, v8
	s_nop 1
	v_cndmask_b32_e32 v39, v139, v39, vcc
	v_cmp_lt_i32_e32 vcc, 0x52, v8
	s_nop 1
	v_cndmask_b32_e32 v40, v139, v40, vcc
	v_cmp_lt_i32_e32 vcc, 0x53, v8
	s_nop 1
	v_cndmask_b32_e32 v41, v139, v41, vcc
	v_cmp_lt_i32_e32 vcc, 0x60, v8
	s_nop 1
	v_cndmask_b32_e32 v42, v139, v42, vcc
	v_cmp_lt_i32_e32 vcc, 0x61, v8
	s_nop 1
	v_cndmask_b32_e32 v43, v139, v43, vcc
	v_cmp_lt_i32_e32 vcc, 0x62, v8
	s_nop 1
	v_cndmask_b32_e32 v44, v139, v44, vcc
	v_cmp_lt_i32_e32 vcc, 0x63, v8
	s_nop 1
	v_cndmask_b32_e32 v45, v139, v45, vcc
	v_cmp_lt_i32_e32 vcc, 0x70, v8
	s_nop 1
	v_cndmask_b32_e32 v46, v139, v46, vcc
	v_cmp_lt_i32_e32 vcc, 0x71, v8
	s_nop 1
	v_cndmask_b32_e32 v47, v139, v47, vcc
	v_cmp_lt_i32_e32 vcc, 0x72, v8
	s_nop 1
	v_cndmask_b32_e32 v48, v139, v48, vcc
	v_cmp_lt_i32_e32 vcc, 0x73, v8
	s_nop 1
	v_cndmask_b32_e32 v49, v139, v49, vcc
	v_cmp_lt_i32_e32 vcc, 0x80, v8
	s_nop 1
	v_cndmask_b32_e32 v50, v139, v50, vcc
	v_cmp_lt_i32_e32 vcc, 0x81, v8
	s_nop 1
	v_cndmask_b32_e32 v51, v139, v51, vcc
	v_cmp_lt_i32_e32 vcc, 0x82, v8
	s_nop 1
	v_cndmask_b32_e32 v52, v139, v52, vcc
	v_cmp_lt_i32_e32 vcc, 0x83, v8
	s_nop 1
	v_cndmask_b32_e32 v53, v139, v53, vcc
	v_cmp_lt_i32_e32 vcc, 0x90, v8
	s_nop 1
	v_cndmask_b32_e32 v54, v139, v54, vcc
	v_cmp_lt_i32_e32 vcc, 0x91, v8
	s_nop 1
	v_cndmask_b32_e32 v55, v139, v55, vcc
	v_cmp_lt_i32_e32 vcc, 0x92, v8
	s_nop 1
	v_cndmask_b32_e32 v56, v139, v56, vcc
	v_cmp_lt_i32_e32 vcc, 0x93, v8
	s_nop 1
	v_cndmask_b32_e32 v57, v139, v57, vcc
	v_cmp_lt_i32_e32 vcc, 0xa0, v8
	s_nop 1
	v_cndmask_b32_e32 v58, v139, v58, vcc
	v_cmp_lt_i32_e32 vcc, 0xa1, v8
	s_nop 1
	v_cndmask_b32_e32 v59, v139, v59, vcc
	v_cmp_lt_i32_e32 vcc, 0xa2, v8
	s_nop 1
	v_cndmask_b32_e32 v60, v139, v60, vcc
	v_cmp_lt_i32_e32 vcc, 0xa3, v8
	s_nop 1
	v_cndmask_b32_e32 v61, v139, v61, vcc
	v_cmp_lt_i32_e32 vcc, 0xb0, v8
	s_nop 1
	v_cndmask_b32_e32 v62, v139, v62, vcc
	v_cmp_lt_i32_e32 vcc, 0xb1, v8
	s_nop 1
	v_cndmask_b32_e32 v63, v139, v63, vcc
	v_cmp_lt_i32_e32 vcc, 0xb2, v8
	s_nop 1
	v_cndmask_b32_e32 v64, v139, v64, vcc
	v_cmp_lt_i32_e32 vcc, 0xb3, v8
	s_nop 1
	v_cndmask_b32_e32 v65, v139, v65, vcc
	v_cmp_lt_i32_e32 vcc, 0xc0, v8
	s_nop 1
	v_cndmask_b32_e32 v66, v139, v66, vcc
	v_cmp_lt_i32_e32 vcc, 0xc1, v8
	s_nop 1
	v_cndmask_b32_e32 v67, v139, v67, vcc
	v_cmp_lt_i32_e32 vcc, 0xc2, v8
	s_nop 1
	v_cndmask_b32_e32 v68, v139, v68, vcc
	v_cmp_lt_i32_e32 vcc, 0xc3, v8
	s_nop 1
	v_cndmask_b32_e32 v69, v139, v69, vcc
	v_cmp_lt_i32_e32 vcc, 0xd0, v8
	s_nop 1
	v_cndmask_b32_e32 v70, v139, v70, vcc
	v_cmp_lt_i32_e32 vcc, 0xd1, v8
	s_nop 1
	v_cndmask_b32_e32 v71, v139, v71, vcc
	v_cmp_lt_i32_e32 vcc, 0xd2, v8
	s_nop 1
	v_cndmask_b32_e32 v72, v139, v72, vcc
	v_cmp_lt_i32_e32 vcc, 0xd3, v8
	s_nop 1
	v_cndmask_b32_e32 v73, v139, v73, vcc
	v_cmp_lt_i32_e32 vcc, 0xe0, v8
	s_nop 1
	v_cndmask_b32_e32 v74, v139, v74, vcc
	v_cmp_lt_i32_e32 vcc, 0xe1, v8
	s_nop 1
	v_cndmask_b32_e32 v75, v139, v75, vcc
	v_cmp_lt_i32_e32 vcc, 0xe2, v8
	s_nop 1
	v_cndmask_b32_e32 v76, v139, v76, vcc
	v_cmp_lt_i32_e32 vcc, 0xe3, v8
	s_nop 1
	v_cndmask_b32_e32 v77, v139, v77, vcc
	v_cmp_lt_i32_e32 vcc, 0xf0, v8
	s_nop 1
	v_cndmask_b32_e32 v78, v139, v78, vcc
	v_cmp_lt_i32_e32 vcc, 0xf1, v8
	s_nop 1
	v_cndmask_b32_e32 v79, v139, v79, vcc
	v_cmp_lt_i32_e32 vcc, 0xf2, v8
	s_nop 1
	v_cndmask_b32_e32 v80, v139, v80, vcc
	v_cmp_lt_i32_e32 vcc, 0xf3, v8
	s_nop 1
	v_cndmask_b32_e32 v81, v139, v81, vcc
